# up-projection epilogue: r2 / sw scale vectors prefetched before the tile's K-loop (3 dependent load-wait groups removed per tile), on top of v24
# speedup vs baseline: 1.0107x; 1.0107x over previous
.LBB0_844:
	s_ashr_i32 s49, s48, 31
	s_lshl_b64 s[50:51], s[48:49], 20
	s_add_u32 s50, s43, s50
	s_addc_u32 s51, s62, s51
	s_and_b64 s[52:53], s[0:1], exec
	s_cselect_b32 s49, s51, s3
	s_cselect_b32 s88, s50, s2
	s_ashr_i32 s47, s46, 31
	s_lshl_b64 s[52:53], s[46:47], 20
	s_add_u32 s52, s8, s52
	s_addc_u32 s53, s9, s53
	s_and_b64 s[58:59], s[0:1], exec
	s_cselect_b32 s47, s53, s57
	s_cselect_b32 s89, s52, s56
	s_add_u32 s90, s56, 0x100
	v_mov_b32_e32 v34, 0
	s_addc_u32 s91, s57, 0
	s_mov_b32 s92, -2
	v_mov_b32_e32 v35, v34
	v_mov_b32_e32 v36, v34
	v_mov_b32_e32 v37, v34
	v_mov_b32_e32 v38, v34
	v_mov_b32_e32 v39, v34
	v_mov_b32_e32 v40, v34
	v_mov_b32_e32 v41, v34
	v_mov_b32_e32 v46, v34
	v_mov_b32_e32 v47, v34
	v_mov_b32_e32 v48, v34
	v_mov_b32_e32 v49, v34
	v_mov_b32_e32 v54, v34
	v_mov_b32_e32 v55, v34
	v_mov_b32_e32 v56, v34
	v_mov_b32_e32 v57, v34
	v_mov_b32_e32 v2, v34
	v_mov_b32_e32 v3, v34
	v_mov_b32_e32 v4, v34
	v_mov_b32_e32 v5, v34
	v_mov_b32_e32 v42, v34
	v_mov_b32_e32 v43, v34
	v_mov_b32_e32 v44, v34
	v_mov_b32_e32 v45, v34
	v_mov_b32_e32 v6, v34
	v_mov_b32_e32 v7, v34
	v_mov_b32_e32 v8, v34
	v_mov_b32_e32 v9, v34
	v_mov_b32_e32 v50, v34
	v_mov_b32_e32 v51, v34
	v_mov_b32_e32 v52, v34
	v_mov_b32_e32 v53, v34
	v_mov_b32_e32 v82, v34
	v_mov_b32_e32 v83, v34
	v_mov_b32_e32 v84, v34
	v_mov_b32_e32 v85, v34
	v_mov_b32_e32 v86, v34
	v_mov_b32_e32 v87, v34
	v_mov_b32_e32 v88, v34
	v_mov_b32_e32 v89, v34
	v_mov_b32_e32 v106, v34
	v_mov_b32_e32 v107, v34
	v_mov_b32_e32 v108, v34
	v_mov_b32_e32 v109, v34
	v_mov_b32_e32 v114, v34
	v_mov_b32_e32 v115, v34
	v_mov_b32_e32 v116, v34
	v_mov_b32_e32 v117, v34
	v_mov_b32_e32 v10, v34
	v_mov_b32_e32 v11, v34
	v_mov_b32_e32 v12, v34
	v_mov_b32_e32 v13, v34
	v_mov_b32_e32 v58, v34
	v_mov_b32_e32 v59, v34
	v_mov_b32_e32 v60, v34
	v_mov_b32_e32 v61, v34
	v_mov_b32_e32 v14, v34
	v_mov_b32_e32 v15, v34
	v_mov_b32_e32 v16, v34
	v_mov_b32_e32 v17, v34
	v_mov_b32_e32 v62, v34
	v_mov_b32_e32 v63, v34
	v_mov_b32_e32 v64, v34
	v_mov_b32_e32 v65, v34
	v_mov_b32_e32 v18, v34
	v_mov_b32_e32 v19, v34
	v_mov_b32_e32 v20, v34
	v_mov_b32_e32 v21, v34
	v_mov_b32_e32 v66, v34
	v_mov_b32_e32 v67, v34
	v_mov_b32_e32 v68, v34
	v_mov_b32_e32 v69, v34
	v_mov_b32_e32 v22, v34
	v_mov_b32_e32 v23, v34
	v_mov_b32_e32 v24, v34
	v_mov_b32_e32 v25, v34
	v_mov_b32_e32 v70, v34
	v_mov_b32_e32 v71, v34
	v_mov_b32_e32 v72, v34
	v_mov_b32_e32 v73, v34
	v_mov_b32_e32 v90, v34
	v_mov_b32_e32 v91, v34
	v_mov_b32_e32 v92, v34
	v_mov_b32_e32 v93, v34
	v_mov_b32_e32 v94, v34
	v_mov_b32_e32 v95, v34
	v_mov_b32_e32 v96, v34
	v_mov_b32_e32 v97, v34
	v_mov_b32_e32 v98, v34
	v_mov_b32_e32 v99, v34
	v_mov_b32_e32 v100, v34
	v_mov_b32_e32 v101, v34
	v_mov_b32_e32 v102, v34
	v_mov_b32_e32 v103, v34
	v_mov_b32_e32 v104, v34
	v_mov_b32_e32 v105, v34
	v_mov_b32_e32 v26, v34
	v_mov_b32_e32 v27, v34
	v_mov_b32_e32 v28, v34
	v_mov_b32_e32 v29, v34
	v_mov_b32_e32 v74, v34
	v_mov_b32_e32 v75, v34
	v_mov_b32_e32 v76, v34
	v_mov_b32_e32 v77, v34
	v_mov_b32_e32 v30, v34
	v_mov_b32_e32 v31, v34
	v_mov_b32_e32 v32, v34
	v_mov_b32_e32 v33, v34
	v_mov_b32_e32 v78, v34
	v_mov_b32_e32 v79, v34
	v_mov_b32_e32 v80, v34
	v_mov_b32_e32 v81, v34
	v_mov_b32_e32 v110, v34
	v_mov_b32_e32 v111, v34
	v_mov_b32_e32 v112, v34
	v_mov_b32_e32 v113, v34
	v_mov_b32_e32 v118, v34
	v_mov_b32_e32 v119, v34
	v_mov_b32_e32 v120, v34
	v_mov_b32_e32 v121, v34
	v_mov_b32_e32 v122, v34
	v_mov_b32_e32 v123, v34
	v_mov_b32_e32 v124, v34
	v_mov_b32_e32 v125, v34
	v_mov_b32_e32 v126, v34
	v_mov_b32_e32 v127, v34
	v_mov_b32_e32 v128, v34
	v_mov_b32_e32 v129, v34
	s_lshl_b32 s98, s54, 10
	s_lshl_b32 s100, s87, 10
	v_lshlrev_b32_e32 v241, 5, v235
	v_lshlrev_b32_e32 v253, 5, v236
	s_add_u32 s98, s45, s98
	s_addc_u32 s99, s80, 0
	s_add_u32 s100, s81, s100
	s_addc_u32 s101, s82, 0
	global_load_dwordx4 v[222:225], v241, s[98:99] offset:16
	global_load_dwordx4 v[226:229], v241, s[98:99]
	global_load_dwordx4 v[230:233], v253, s[100:101] offset:16
	global_load_dwordx4 v[242:245], v253, s[100:101]
	global_load_dwordx4 v[246:249], v253, s[100:101] offset:528
	global_load_dwordx2 v[250:251], v253, s[100:101] offset:512
	global_load_dwordx2 v[254:255], v253, s[100:101] offset:520

.LBB0_848:
	s_lshl_b32 s56, s54, 8
	s_ashr_i32 s57, s56, 31
	v_mov_b32_e32 v159, v235
	v_mov_b32_e32 v158, v236
	s_lshl_b64 s[2:3], s[56:57], 2
	s_add_u32 s2, s45, s2
	v_lshlrev_b32_e32 v220, 3, v159
	s_addc_u32 s3, s80, s3
	v_ashrrev_i32_e32 v221, 31, v220
	v_cvt_f32_i32_e32 v133, v87
	v_cvt_f32_i32_e32 v132, v86
	v_lshl_add_u64 v[86:87], v[220:221], 2, s[2:3]
	v_cvt_f32_i32_e32 v131, v89
	v_cvt_f32_i32_e32 v130, v88
	v_cvt_f32_i32_e32 v135, v85
	v_cvt_f32_i32_e32 v134, v84
	v_cvt_f32_i32_e32 v137, v83
	v_cvt_f32_i32_e32 v136, v82
	v_mov_b64_e32 v[82:83], v[222:223]
	v_mov_b64_e32 v[84:85], v[224:225]
	s_nop 0
	v_mov_b64_e32 v[86:87], v[226:227]
	v_mov_b64_e32 v[88:89], v[228:229]
	s_lshl_b32 s2, s87, 8
	s_ashr_i32 s3, s2, 31
	v_cvt_f32_i32_e32 v109, v109
	v_cvt_f32_i32_e32 v108, v108
	v_cvt_f32_i32_e32 v107, v107
	v_cvt_f32_i32_e32 v106, v106
	s_lshl_b64 s[58:59], s[2:3], 2
	v_lshlrev_b32_e32 v154, 3, v158
	s_add_u32 s58, s81, s58
	v_ashrrev_i32_e32 v155, 31, v154
	s_addc_u32 s59, s82, s59
	v_lshl_add_u64 v[152:153], v[154:155], 2, s[58:59]
	v_cvt_f32_i32_e32 v117, v117
	v_cvt_f32_i32_e32 v116, v116
	v_cvt_f32_i32_e32 v115, v115
	v_cvt_f32_i32_e32 v114, v114
	v_cvt_f32_i32_e32 v57, v57
	v_cvt_f32_i32_e32 v56, v56
	v_cvt_f32_i32_e32 v55, v55
	v_cvt_f32_i32_e32 v54, v54
	v_cvt_f32_i32_e32 v49, v49
	v_cvt_f32_i32_e32 v48, v48
	v_cvt_f32_i32_e32 v47, v47
	v_cvt_f32_i32_e32 v46, v46
	v_cvt_f32_i32_e32 v41, v41
	v_cvt_f32_i32_e32 v40, v40
	v_cvt_f32_i32_e32 v39, v39
	v_cvt_f32_i32_e32 v38, v38
	v_cvt_f32_i32_e32 v37, v37
	v_cvt_f32_i32_e32 v36, v36
	v_cvt_f32_i32_e32 v35, v35
	v_cvt_f32_i32_e32 v34, v34
	s_or_b32 s2, s2, s77
	v_cmp_eq_u32_e32 vcc, 15, v159
	s_and_b64 s[58:59], s[10:11], vcc
	s_mul_i32 s47, s54, 0x2b000
	v_pk_mul_f32 v[138:139], v[84:85], v[106:107] op_sel_hi:[0,1]
	v_pk_mul_f32 v[140:141], v[84:85], v[108:109] op_sel_hi:[0,1]
	v_mov_b64_e32 v[106:107], v[230:231]
	v_mov_b64_e32 v[108:109], v[232:233]
	v_mov_b64_e32 v[146:147], v[242:243]
	v_mov_b64_e32 v[148:149], v[244:245]
	v_pk_mul_f32 v[114:115], v[84:85], v[114:115] op_sel_hi:[0,1]
	v_pk_mul_f32 v[116:117], v[84:85], v[116:117] op_sel_hi:[0,1]
	v_pk_mul_f32 v[54:55], v[84:85], v[54:55] op_sel_hi:[0,1]
	v_pk_mul_f32 v[56:57], v[84:85], v[56:57] op_sel_hi:[0,1]
	v_pk_mul_f32 v[46:47], v[84:85], v[46:47] op_sel_hi:[0,1]
	v_pk_mul_f32 v[48:49], v[84:85], v[48:49] op_sel_hi:[0,1]
	v_mov_b32_e32 v84, v85
	v_pk_mul_f32 v[150:151], v[84:85], v[134:135] op_sel_hi:[0,1]
	v_pk_mul_f32 v[142:143], v[84:85], v[132:133] op_sel_hi:[0,1]
	v_pk_mul_f32 v[130:131], v[84:85], v[130:131] op_sel_hi:[0,1]
	v_pk_mul_f32 v[144:145], v[84:85], v[136:137] op_sel_hi:[0,1]
	v_pk_mul_f32 v[156:157], v[84:85], v[38:39] op_sel_hi:[0,1]
	v_pk_mul_f32 v[160:161], v[84:85], v[40:41] op_sel_hi:[0,1]
	v_pk_mul_f32 v[162:163], v[84:85], v[34:35] op_sel_hi:[0,1]
	v_pk_mul_f32 v[84:85], v[84:85], v[36:37] op_sel_hi:[0,1]
	v_pk_mul_f32 v[36:37], v[150:151], v[108:109]
	v_pk_mul_f32 v[136:137], v[148:149], v[116:117]
	v_pk_mul_f32 v[134:135], v[146:147], v[114:115]
	v_mov_b64_e32 v[114:115], v[246:247]
	v_mov_b64_e32 v[116:117], v[248:249]
	s_nop 0
	v_mov_b64_e32 v[150:151], v[250:251]
	v_mov_b64_e32 v[152:153], v[254:255]
	v_pk_mul_f32 v[38:39], v[138:139], v[106:107]
	v_pk_mul_f32 v[132:133], v[148:149], v[130:131]
	v_pk_mul_f32 v[130:131], v[146:147], v[142:143]
	v_pk_mul_f32 v[40:41], v[140:141], v[108:109]
	v_pk_mul_f32 v[34:35], v[144:145], v[106:107]
	v_pk_mul_f32 v[138:139], v[156:157], v[150:151]
	v_add_u32_e32 v156, s2, v154
	v_pk_mul_f32 v[144:145], v[56:57], v[152:153]
	v_pk_mul_f32 v[142:143], v[54:55], v[150:151]
	v_pk_mul_f32 v[140:141], v[160:161], v[152:153]
	v_pk_mul_f32 v[56:57], v[48:49], v[116:117]
	v_pk_mul_f32 v[54:55], v[46:47], v[114:115]
	v_pk_mul_f32 v[48:49], v[84:85], v[116:117]
	v_pk_mul_f32 v[46:47], v[162:163], v[114:115]
	v_ashrrev_i32_e32 v157, 31, v156
	s_and_saveexec_b64 s[2:3], s[58:59]
	v_readlane_b32 s89, v252, 18
	s_cbranch_execz .LBB0_850
	s_lshl_b32 s49, s54, 1
	s_mul_hi_i32 s57, s49, 0x15800
	s_add_u32 s58, s73, s47
	s_addc_u32 s59, s74, s57
	s_or_b32 s49, s49, 1
	v_lshlrev_b64 v[84:85], 2, v[156:157]
	s_mul_hi_i32 s57, s49, 0x15800
	s_mul_i32 s49, s49, 0x15800
	v_lshl_add_u64 v[160:161], s[58:59], 0, v[84:85]
	s_add_u32 s58, s73, s49
	s_addc_u32 s59, s74, s57
	v_lshl_add_u64 v[84:85], s[58:59], 0, v[84:85]
	global_store_dwordx4 v[160:161], v[134:137], off
	global_store_dwordx4 v[160:161], v[38:41], off offset:16
	global_store_dwordx4 v[160:161], v[142:145], off offset:512
	global_store_dwordx4 v[160:161], v[54:57], off offset:528
	global_store_dwordx4 v[84:85], v[130:133], off
	global_store_dwordx4 v[84:85], v[34:37], off offset:16
	global_store_dwordx4 v[84:85], v[138:141], off offset:512
	global_store_dwordx4 v[84:85], v[46:49], off offset:528

.LBB0_1696:
	s_ashr_i32 s49, s48, 31
	s_lshl_b64 s[50:51], s[48:49], 20
	s_add_u32 s50, s62, s50
	s_addc_u32 s51, s63, s51
	s_and_b64 s[52:53], s[0:1], exec
	s_cselect_b32 s49, s51, s3
	s_cselect_b32 s87, s50, s2
	s_ashr_i32 s47, s46, 31
	s_lshl_b64 s[52:53], s[46:47], 20
	s_add_u32 s52, s8, s52
	s_addc_u32 s53, s9, s53
	s_and_b64 s[58:59], s[0:1], exec
	s_cselect_b32 s47, s53, s57
	s_cselect_b32 s88, s52, s56
	s_add_u32 s89, s56, 0x100
	v_mov_b32_e32 v34, 0
	s_addc_u32 s90, s57, 0
	s_mov_b32 s91, -2
	v_mov_b32_e32 v35, v34
	v_mov_b32_e32 v36, v34
	v_mov_b32_e32 v37, v34
	v_mov_b32_e32 v38, v34
	v_mov_b32_e32 v39, v34
	v_mov_b32_e32 v40, v34
	v_mov_b32_e32 v41, v34
	v_mov_b32_e32 v46, v34
	v_mov_b32_e32 v47, v34
	v_mov_b32_e32 v48, v34
	v_mov_b32_e32 v49, v34
	v_mov_b32_e32 v54, v34
	v_mov_b32_e32 v55, v34
	v_mov_b32_e32 v56, v34
	v_mov_b32_e32 v57, v34
	v_mov_b32_e32 v2, v34
	v_mov_b32_e32 v3, v34
	v_mov_b32_e32 v4, v34
	v_mov_b32_e32 v5, v34
	v_mov_b32_e32 v42, v34
	v_mov_b32_e32 v43, v34
	v_mov_b32_e32 v44, v34
	v_mov_b32_e32 v45, v34
	v_mov_b32_e32 v6, v34
	v_mov_b32_e32 v7, v34
	v_mov_b32_e32 v8, v34
	v_mov_b32_e32 v9, v34
	v_mov_b32_e32 v50, v34
	v_mov_b32_e32 v51, v34
	v_mov_b32_e32 v52, v34
	v_mov_b32_e32 v53, v34
	v_mov_b32_e32 v82, v34
	v_mov_b32_e32 v83, v34
	v_mov_b32_e32 v84, v34
	v_mov_b32_e32 v85, v34
	v_mov_b32_e32 v86, v34
	v_mov_b32_e32 v87, v34
	v_mov_b32_e32 v88, v34
	v_mov_b32_e32 v89, v34
	v_mov_b32_e32 v106, v34
	v_mov_b32_e32 v107, v34
	v_mov_b32_e32 v108, v34
	v_mov_b32_e32 v109, v34
	v_mov_b32_e32 v114, v34
	v_mov_b32_e32 v115, v34
	v_mov_b32_e32 v116, v34
	v_mov_b32_e32 v117, v34
	v_mov_b32_e32 v10, v34
	v_mov_b32_e32 v11, v34
	v_mov_b32_e32 v12, v34
	v_mov_b32_e32 v13, v34
	v_mov_b32_e32 v58, v34
	v_mov_b32_e32 v59, v34
	v_mov_b32_e32 v60, v34
	v_mov_b32_e32 v61, v34
	v_mov_b32_e32 v14, v34
	v_mov_b32_e32 v15, v34
	v_mov_b32_e32 v16, v34
	v_mov_b32_e32 v17, v34
	v_mov_b32_e32 v62, v34
	v_mov_b32_e32 v63, v34
	v_mov_b32_e32 v64, v34
	v_mov_b32_e32 v65, v34
	v_mov_b32_e32 v18, v34
	v_mov_b32_e32 v19, v34
	v_mov_b32_e32 v20, v34
	v_mov_b32_e32 v21, v34
	v_mov_b32_e32 v66, v34
	v_mov_b32_e32 v67, v34
	v_mov_b32_e32 v68, v34
	v_mov_b32_e32 v69, v34
	v_mov_b32_e32 v22, v34
	v_mov_b32_e32 v23, v34
	v_mov_b32_e32 v24, v34
	v_mov_b32_e32 v25, v34
	v_mov_b32_e32 v70, v34
	v_mov_b32_e32 v71, v34
	v_mov_b32_e32 v72, v34
	v_mov_b32_e32 v73, v34
	v_mov_b32_e32 v90, v34
	v_mov_b32_e32 v91, v34
	v_mov_b32_e32 v92, v34
	v_mov_b32_e32 v93, v34
	v_mov_b32_e32 v94, v34
	v_mov_b32_e32 v95, v34
	v_mov_b32_e32 v96, v34
	v_mov_b32_e32 v97, v34
	v_mov_b32_e32 v98, v34
	v_mov_b32_e32 v99, v34
	v_mov_b32_e32 v100, v34
	v_mov_b32_e32 v101, v34
	v_mov_b32_e32 v102, v34
	v_mov_b32_e32 v103, v34
	v_mov_b32_e32 v104, v34
	v_mov_b32_e32 v105, v34
	v_mov_b32_e32 v26, v34
	v_mov_b32_e32 v27, v34
	v_mov_b32_e32 v28, v34
	v_mov_b32_e32 v29, v34
	v_mov_b32_e32 v74, v34
	v_mov_b32_e32 v75, v34
	v_mov_b32_e32 v76, v34
	v_mov_b32_e32 v77, v34
	v_mov_b32_e32 v30, v34
	v_mov_b32_e32 v31, v34
	v_mov_b32_e32 v32, v34
	v_mov_b32_e32 v33, v34
	v_mov_b32_e32 v78, v34
	v_mov_b32_e32 v79, v34
	v_mov_b32_e32 v80, v34
	v_mov_b32_e32 v81, v34
	v_mov_b32_e32 v110, v34
	v_mov_b32_e32 v111, v34
	v_mov_b32_e32 v112, v34
	v_mov_b32_e32 v113, v34
	v_mov_b32_e32 v118, v34
	v_mov_b32_e32 v119, v34
	v_mov_b32_e32 v120, v34
	v_mov_b32_e32 v121, v34
	v_mov_b32_e32 v122, v34
	v_mov_b32_e32 v123, v34
	v_mov_b32_e32 v124, v34
	v_mov_b32_e32 v125, v34
	v_mov_b32_e32 v126, v34
	v_mov_b32_e32 v127, v34
	v_mov_b32_e32 v128, v34
	v_mov_b32_e32 v129, v34
	s_lshl_b32 s98, s54, 10
	s_lshl_b32 s100, s86, 10
	v_lshlrev_b32_e32 v241, 5, v235
	v_lshlrev_b32_e32 v253, 5, v236
	s_add_u32 s98, s45, s98
	s_addc_u32 s99, s79, 0
	s_add_u32 s100, s80, s100
	s_addc_u32 s101, s81, 0
	global_load_dwordx4 v[222:225], v241, s[98:99] offset:16
	global_load_dwordx4 v[226:229], v241, s[98:99]
	global_load_dwordx4 v[230:233], v253, s[100:101] offset:16
	global_load_dwordx4 v[242:245], v253, s[100:101]
	global_load_dwordx4 v[246:249], v253, s[100:101] offset:528
	global_load_dwordx2 v[250:251], v253, s[100:101] offset:512
	global_load_dwordx2 v[254:255], v253, s[100:101] offset:520

.LBB0_1700:
	s_lshl_b32 s56, s54, 8
	s_ashr_i32 s57, s56, 31
	v_mov_b32_e32 v159, v235
	v_mov_b32_e32 v158, v236
	s_lshl_b64 s[2:3], s[56:57], 2
	s_add_u32 s2, s45, s2
	v_lshlrev_b32_e32 v220, 3, v159
	s_addc_u32 s3, s79, s3
	v_ashrrev_i32_e32 v221, 31, v220
	v_cvt_f32_i32_e32 v133, v87
	v_cvt_f32_i32_e32 v132, v86
	v_lshl_add_u64 v[86:87], v[220:221], 2, s[2:3]
	v_cvt_f32_i32_e32 v131, v89
	v_cvt_f32_i32_e32 v130, v88
	v_cvt_f32_i32_e32 v135, v85
	v_cvt_f32_i32_e32 v134, v84
	v_cvt_f32_i32_e32 v137, v83
	v_cvt_f32_i32_e32 v136, v82
	v_mov_b64_e32 v[82:83], v[222:223]
	v_mov_b64_e32 v[84:85], v[224:225]
	s_nop 0
	v_mov_b64_e32 v[86:87], v[226:227]
	v_mov_b64_e32 v[88:89], v[228:229]
	s_lshl_b32 s2, s86, 8
	s_ashr_i32 s3, s2, 31
	v_cvt_f32_i32_e32 v109, v109
	v_cvt_f32_i32_e32 v108, v108
	v_cvt_f32_i32_e32 v107, v107
	v_cvt_f32_i32_e32 v106, v106
	s_lshl_b64 s[58:59], s[2:3], 2
	v_lshlrev_b32_e32 v154, 3, v158
	s_add_u32 s58, s80, s58
	v_ashrrev_i32_e32 v155, 31, v154
	s_addc_u32 s59, s81, s59
	v_lshl_add_u64 v[152:153], v[154:155], 2, s[58:59]
	v_cvt_f32_i32_e32 v117, v117
	v_cvt_f32_i32_e32 v116, v116
	v_cvt_f32_i32_e32 v115, v115
	v_cvt_f32_i32_e32 v114, v114
	v_cvt_f32_i32_e32 v57, v57
	v_cvt_f32_i32_e32 v56, v56
	v_cvt_f32_i32_e32 v55, v55
	v_cvt_f32_i32_e32 v54, v54
	v_cvt_f32_i32_e32 v49, v49
	v_cvt_f32_i32_e32 v48, v48
	v_cvt_f32_i32_e32 v47, v47
	v_cvt_f32_i32_e32 v46, v46
	v_cvt_f32_i32_e32 v41, v41
	v_cvt_f32_i32_e32 v40, v40
	v_cvt_f32_i32_e32 v39, v39
	v_cvt_f32_i32_e32 v38, v38
	v_cvt_f32_i32_e32 v37, v37
	v_cvt_f32_i32_e32 v36, v36
	v_cvt_f32_i32_e32 v35, v35
	v_cvt_f32_i32_e32 v34, v34
	s_or_b32 s2, s2, s76
	v_cmp_eq_u32_e32 vcc, 15, v159
	s_and_b64 s[58:59], s[12:13], vcc
	s_mul_i32 s47, s54, 0x2b000
	v_pk_mul_f32 v[138:139], v[84:85], v[106:107] op_sel_hi:[0,1]
	v_pk_mul_f32 v[140:141], v[84:85], v[108:109] op_sel_hi:[0,1]
	v_mov_b64_e32 v[106:107], v[230:231]
	v_mov_b64_e32 v[108:109], v[232:233]
	v_mov_b64_e32 v[146:147], v[242:243]
	v_mov_b64_e32 v[148:149], v[244:245]
	v_pk_mul_f32 v[114:115], v[84:85], v[114:115] op_sel_hi:[0,1]
	v_pk_mul_f32 v[116:117], v[84:85], v[116:117] op_sel_hi:[0,1]
	v_pk_mul_f32 v[54:55], v[84:85], v[54:55] op_sel_hi:[0,1]
	v_pk_mul_f32 v[56:57], v[84:85], v[56:57] op_sel_hi:[0,1]
	v_pk_mul_f32 v[46:47], v[84:85], v[46:47] op_sel_hi:[0,1]
	v_pk_mul_f32 v[48:49], v[84:85], v[48:49] op_sel_hi:[0,1]
	v_mov_b32_e32 v84, v85
	v_pk_mul_f32 v[150:151], v[84:85], v[134:135] op_sel_hi:[0,1]
	v_pk_mul_f32 v[142:143], v[84:85], v[132:133] op_sel_hi:[0,1]
	v_pk_mul_f32 v[130:131], v[84:85], v[130:131] op_sel_hi:[0,1]
	v_pk_mul_f32 v[144:145], v[84:85], v[136:137] op_sel_hi:[0,1]
	v_pk_mul_f32 v[156:157], v[84:85], v[38:39] op_sel_hi:[0,1]
	v_pk_mul_f32 v[160:161], v[84:85], v[40:41] op_sel_hi:[0,1]
	v_pk_mul_f32 v[162:163], v[84:85], v[34:35] op_sel_hi:[0,1]
	v_pk_mul_f32 v[84:85], v[84:85], v[36:37] op_sel_hi:[0,1]
	v_pk_mul_f32 v[36:37], v[150:151], v[108:109]
	v_pk_mul_f32 v[136:137], v[148:149], v[116:117]
	v_pk_mul_f32 v[134:135], v[146:147], v[114:115]
	v_mov_b64_e32 v[114:115], v[246:247]
	v_mov_b64_e32 v[116:117], v[248:249]
	s_nop 0
	v_mov_b64_e32 v[150:151], v[250:251]
	v_mov_b64_e32 v[152:153], v[254:255]
	v_pk_mul_f32 v[38:39], v[138:139], v[106:107]
	v_pk_mul_f32 v[132:133], v[148:149], v[130:131]
	v_pk_mul_f32 v[130:131], v[146:147], v[142:143]
	v_pk_mul_f32 v[40:41], v[140:141], v[108:109]
	v_pk_mul_f32 v[34:35], v[144:145], v[106:107]
	v_pk_mul_f32 v[138:139], v[156:157], v[150:151]
	v_add_u32_e32 v156, s2, v154
	v_pk_mul_f32 v[144:145], v[56:57], v[152:153]
	v_pk_mul_f32 v[142:143], v[54:55], v[150:151]
	v_pk_mul_f32 v[140:141], v[160:161], v[152:153]
	v_pk_mul_f32 v[56:57], v[48:49], v[116:117]
	v_pk_mul_f32 v[54:55], v[46:47], v[114:115]
	v_pk_mul_f32 v[48:49], v[84:85], v[116:117]
	v_pk_mul_f32 v[46:47], v[162:163], v[114:115]
	v_ashrrev_i32_e32 v157, 31, v156
	s_and_saveexec_b64 s[2:3], s[58:59]
	v_readlane_b32 s87, v252, 18
	s_cbranch_execz .LBB0_1702
	s_lshl_b32 s43, s54, 1
	s_mul_hi_i32 s49, s43, 0x15800
	s_add_u32 s58, s72, s47
	s_addc_u32 s59, s73, s49
	s_or_b32 s43, s43, 1
	v_lshlrev_b64 v[84:85], 2, v[156:157]
	s_mul_hi_i32 s49, s43, 0x15800
	s_mul_i32 s43, s43, 0x15800
	v_lshl_add_u64 v[160:161], s[58:59], 0, v[84:85]
	s_add_u32 s58, s72, s43
	s_addc_u32 s59, s73, s49
	v_lshl_add_u64 v[84:85], s[58:59], 0, v[84:85]
	global_store_dwordx4 v[160:161], v[134:137], off
	global_store_dwordx4 v[160:161], v[38:41], off offset:16
	global_store_dwordx4 v[160:161], v[142:145], off offset:512
	global_store_dwordx4 v[160:161], v[54:57], off offset:528
	global_store_dwordx4 v[84:85], v[130:133], off
	global_store_dwordx4 v[84:85], v[34:37], off offset:16
	global_store_dwordx4 v[84:85], v[138:141], off offset:512
	global_store_dwordx4 v[84:85], v[46:49], off offset:528

	.amdhsa_kernel _Z3fwd4Args
		.amdhsa_group_segment_fixed_size 0
		.amdhsa_private_segment_fixed_size 0
		.amdhsa_kernarg_size 464
		.amdhsa_user_sgpr_count 2
		.amdhsa_user_sgpr_dispatch_ptr 0
		.amdhsa_user_sgpr_queue_ptr 0
		.amdhsa_user_sgpr_kernarg_segment_ptr 1
		.amdhsa_user_sgpr_dispatch_id 0
		.amdhsa_user_sgpr_kernarg_preload_length 0
		.amdhsa_user_sgpr_kernarg_preload_offset 0
		.amdhsa_user_sgpr_private_segment_size 0
		.amdhsa_uses_dynamic_stack 0
		.amdhsa_enable_private_segment 0
		.amdhsa_system_sgpr_workgroup_id_x 1
		.amdhsa_system_sgpr_workgroup_id_y 0
		.amdhsa_system_sgpr_workgroup_id_z 0
		.amdhsa_system_sgpr_workgroup_info 0
		.amdhsa_system_vgpr_workitem_id 0
		.amdhsa_next_free_vgpr 256
		.amdhsa_next_free_sgpr 102
		.amdhsa_accum_offset 256
		.amdhsa_reserve_vcc 1
		.amdhsa_float_round_mode_32 0
		.amdhsa_float_round_mode_16_64 0
		.amdhsa_float_denorm_mode_32 3
		.amdhsa_float_denorm_mode_16_64 3
		.amdhsa_dx10_clamp 1
		.amdhsa_ieee_mode 1
		.amdhsa_fp16_overflow 0
		.amdhsa_tg_split 0
		.amdhsa_exception_fp_ieee_invalid_op 0
		.amdhsa_exception_fp_denorm_src 0
		.amdhsa_exception_fp_ieee_div_zero 0
		.amdhsa_exception_fp_ieee_overflow 0
		.amdhsa_exception_fp_ieee_underflow 0
		.amdhsa_exception_fp_ieee_inexact 0
		.amdhsa_exception_int_div_zero 0
	.end_amdhsa_kernel

amdhsa.kernels:
  - .agpr_count:     0
    .args:
      - .offset:         0
        .size:           208
        .value_kind:     by_value
      - .offset:         208
        .size:           4
        .value_kind:     hidden_block_count_x
      - .offset:         212
        .size:           4
        .value_kind:     hidden_block_count_y
      - .offset:         216
        .size:           4
        .value_kind:     hidden_block_count_z
      - .offset:         220
        .size:           2
        .value_kind:     hidden_group_size_x
      - .offset:         222
        .size:           2
        .value_kind:     hidden_group_size_y
      - .offset:         224
        .size:           2
        .value_kind:     hidden_group_size_z
      - .offset:         226
        .size:           2
        .value_kind:     hidden_remainder_x
      - .offset:         228
        .size:           2
        .value_kind:     hidden_remainder_y
      - .offset:         230
        .size:           2
        .value_kind:     hidden_remainder_z
      - .offset:         248
        .size:           8
        .value_kind:     hidden_global_offset_x
      - .offset:         256
        .size:           8
        .value_kind:     hidden_global_offset_y
      - .offset:         264
        .size:           8
        .value_kind:     hidden_global_offset_z
      - .offset:         272
        .size:           2
        .value_kind:     hidden_grid_dims
      - .offset:         328
        .size:           4
        .value_kind:     hidden_dynamic_lds_size
    .group_segment_fixed_size: 0
    .kernarg_segment_align: 8
    .kernarg_segment_size: 464
    .language:       OpenCL C
    .language_version:
      - 2
      - 0
    .max_flat_workgroup_size: 512
    .name:           _Z3fwd4Args
    .private_segment_fixed_size: 0
    .sgpr_count:     108
    .sgpr_spill_count: 186
    .symbol:         _Z3fwd4Args.kd
    .uniform_work_group_size: 1
    .uses_dynamic_stack: false
    .vgpr_count:     256
    .vgpr_spill_count: 0
    .wavefront_size: 64
